# FFN_UP SwiGLU epilogue rewritten by hand: rstd values read up front, in-place packed math on dead accumulators, one base address + immediate offsets; no vmcnt(0) drain at epilogue top
# baseline (speedup 1.0000x reference)
; DI u32x2 pk4(f32x4 v) { u32x2 r; r.x = cvt_pk(v[0], v[1]); r.y = cvt_pk(v[2], v[3]); return r; }
; DI float fexp2(float x) { return __builtin_amdgcn_exp2f(x); }
; DI float frcp(float x) { return __builtin_amdgcn_rcpf(x); }
; DI void gemm_phase(LAS unsigned char* lds, const GemmDesc& d, float* __restrict__ X) {
;     ...
;     if (EPI_ON(EPI_FFN_UP)) {
; #pragma unroll
;       for (int ai = 0; ai < 2; ++ai)
; #pragma unroll
;         for (int m = 0; m < 4; ++m) {
;           const int row = pm * 256 + 128 * ai + 16 * m + rb; const float rs = rsl[128 * ai + 16 * m + rb]; const float c1 = -rs * LOG2E, c2 = rs * rs;
;           u32x2 hp[2];
; #pragma unroll
;           for (int n = 0; n < 2; ++n) {
;             const f32x4 G = acc[ai][0][m][n], U = acc[ai][1][m][n]; const f32x4 tt = G * c1; f32x4 ee;
; #pragma unroll
;             for (int j = 0; j < 4; ++j) ee[j] = fexp2(tt[j]);
;             const f32x4 dn = ee + 1.f; f32x4 rr;
; #pragma unroll
;             for (int j = 0; j < 4; ++j) rr[j] = frcp(dn[j]);
;             hp[n] = pk4((G * U) * (rr * c2));
;           }
;           { const int hc = pn * 128 + cb;
;             u32x4 hw; hw.x = hp[0].x; hw.y = hp[0].y; hw.z = hp[1].x; hw.w = hp[1].y;
;             *(u32x4*)(d.O0 + (size_t)(row >> 8) * (256 * FF) + (size_t)(hc >> 6) * (256 * 64) + (row & 255) * 64 + (hc & 63)) = hw; }
;           asm volatile("" ::: "memory");
;         }
.LBB0_519:
	s_andn2_b64 vcc, exec, s[44:45]
	s_cbranch_vccnz .LBB0_542
	s_cmp_lg_u32 s24, 1
	s_mov_b64 s[44:45], -1
	s_cbranch_scc0 .LBB0_522
	v_lshl_add_u32 v141, v163, 2, s38
	ds_read_b32 v132, v141
	ds_read_b32 v133, v141 offset:64
	ds_read_b32 v134, v141 offset:128
	ds_read_b32 v135, v141 offset:192
	ds_read_b32 v136, v141 offset:512
	ds_read_b32 v137, v141 offset:576
	ds_read_b32 v138, v141 offset:640
	ds_read_b32 v139, v141 offset:704
	s_lshl_b32 s6, s68, 7
	v_lshl_add_u32 v0, s97, 8, v163
	s_or_b32 s6, s21, s6
	v_lshrrev_b32_e32 v0, 8, v0
	s_ashr_i32 s14, s6, 6
	v_mul_hi_i32_i24_e32 v131, 0x160000, v0
	v_mul_i32_i24_e32 v130, 0x160000, v0
	s_ashr_i32 s15, s14, 31
	v_lshl_add_u64 v[130:131], s[28:29], 0, v[130:131]
	s_lshl_b64 s[44:45], s[14:15], 15
	v_lshlrev_b32_e32 v0, 7, v163
	v_and_b32_e32 v144, 56, v182
	v_lshl_add_u64 v[130:131], v[130:131], 0, s[44:45]
	v_and_b32_e32 v0, 0x6780, v0
	v_lshl_add_u64 v[130:131], v[130:131], 0, v[0:1]
	v_lshlrev_b32_e32 v0, 1, v144
	v_mov_b32_e32 v144, 1.0
	v_lshl_add_u64 v[130:131], v[130:131], 0, v[0:1]
	v_mov_b32_e32 v145, 1.0
	s_mov_b32 s15, 0
	s_waitcnt lgkmcnt(0)
	v_mul_f32_e32 v140, 0xbfb8aa3b, v132
	v_mul_f32_e32 v142, v132, v132
	v_pk_mul_f32 v[118:119], v[126:127], v[118:119]
	v_pk_mul_f32 v[120:121], v[128:129], v[120:121]
	v_pk_mul_f32 v[114:115], v[122:123], v[114:115]
	v_pk_mul_f32 v[116:117], v[124:125], v[116:117]
	v_pk_mul_f32 v[126:127], v[126:127], v[140:141] op_sel_hi:[1,0]
	v_pk_mul_f32 v[128:129], v[128:129], v[140:141] op_sel_hi:[1,0]
	v_pk_mul_f32 v[122:123], v[122:123], v[140:141] op_sel_hi:[1,0]
	v_pk_mul_f32 v[124:125], v[124:125], v[140:141] op_sel_hi:[1,0]
	v_exp_f32_e32 v126, v126
	v_exp_f32_e32 v127, v127
	v_exp_f32_e32 v128, v128
	v_exp_f32_e32 v129, v129
	v_exp_f32_e32 v122, v122
	v_exp_f32_e32 v123, v123
	v_exp_f32_e32 v124, v124
	v_exp_f32_e32 v125, v125
	v_pk_add_f32 v[126:127], v[126:127], v[144:145]
	v_pk_add_f32 v[128:129], v[128:129], v[144:145]
	v_pk_add_f32 v[122:123], v[122:123], v[144:145]
	v_pk_add_f32 v[124:125], v[124:125], v[144:145]
	v_rcp_f32_e32 v126, v126
	v_rcp_f32_e32 v127, v127
	v_rcp_f32_e32 v128, v128
	v_rcp_f32_e32 v129, v129
	v_rcp_f32_e32 v122, v122
	v_rcp_f32_e32 v123, v123
	v_rcp_f32_e32 v124, v124
	v_rcp_f32_e32 v125, v125
	v_pk_mul_f32 v[126:127], v[142:143], v[126:127] op_sel_hi:[0,1]
	v_pk_mul_f32 v[128:129], v[142:143], v[128:129] op_sel_hi:[0,1]
	v_pk_mul_f32 v[122:123], v[142:143], v[122:123] op_sel_hi:[0,1]
	v_pk_mul_f32 v[124:125], v[142:143], v[124:125] op_sel_hi:[0,1]
	v_pk_mul_f32 v[126:127], v[118:119], v[126:127]
	v_pk_mul_f32 v[128:129], v[120:121], v[128:129]
	v_pk_mul_f32 v[122:123], v[114:115], v[122:123]
	v_pk_mul_f32 v[124:125], v[116:117], v[124:125]
	v_cvt_pk_bf16_f32 v126, v126, v127
	v_cvt_pk_bf16_f32 v127, v128, v129
	v_cvt_pk_bf16_f32 v128, v122, v123
	v_cvt_pk_bf16_f32 v129, v124, v125
	global_store_dwordx4 v[130:131], v[126:129], off
	v_mul_f32_e32 v140, 0xbfb8aa3b, v133
	v_mul_f32_e32 v142, v133, v133
	v_pk_mul_f32 v[102:103], v[110:111], v[102:103]
	v_pk_mul_f32 v[104:105], v[112:113], v[104:105]
	v_pk_mul_f32 v[98:99], v[106:107], v[98:99]
	v_pk_mul_f32 v[100:101], v[108:109], v[100:101]
	v_pk_mul_f32 v[110:111], v[110:111], v[140:141] op_sel_hi:[1,0]
	v_pk_mul_f32 v[112:113], v[112:113], v[140:141] op_sel_hi:[1,0]
	v_pk_mul_f32 v[106:107], v[106:107], v[140:141] op_sel_hi:[1,0]
	v_pk_mul_f32 v[108:109], v[108:109], v[140:141] op_sel_hi:[1,0]
	v_exp_f32_e32 v110, v110
	v_exp_f32_e32 v111, v111
	v_exp_f32_e32 v112, v112
	v_exp_f32_e32 v113, v113
	v_exp_f32_e32 v106, v106
	v_exp_f32_e32 v107, v107
	v_exp_f32_e32 v108, v108
	v_exp_f32_e32 v109, v109
	v_pk_add_f32 v[110:111], v[110:111], v[144:145]
	v_pk_add_f32 v[112:113], v[112:113], v[144:145]
	v_pk_add_f32 v[106:107], v[106:107], v[144:145]
	v_pk_add_f32 v[108:109], v[108:109], v[144:145]
	v_rcp_f32_e32 v110, v110
	v_rcp_f32_e32 v111, v111
	v_rcp_f32_e32 v112, v112
	v_rcp_f32_e32 v113, v113
	v_rcp_f32_e32 v106, v106
	v_rcp_f32_e32 v107, v107
	v_rcp_f32_e32 v108, v108
	v_rcp_f32_e32 v109, v109
	v_pk_mul_f32 v[110:111], v[142:143], v[110:111] op_sel_hi:[0,1]
	v_pk_mul_f32 v[112:113], v[142:143], v[112:113] op_sel_hi:[0,1]
	v_pk_mul_f32 v[106:107], v[142:143], v[106:107] op_sel_hi:[0,1]
	v_pk_mul_f32 v[108:109], v[142:143], v[108:109] op_sel_hi:[0,1]
	v_pk_mul_f32 v[110:111], v[102:103], v[110:111]
	v_pk_mul_f32 v[112:113], v[104:105], v[112:113]
	v_pk_mul_f32 v[106:107], v[98:99], v[106:107]
	v_pk_mul_f32 v[108:109], v[100:101], v[108:109]
	v_cvt_pk_bf16_f32 v110, v110, v111
	v_cvt_pk_bf16_f32 v111, v112, v113
	v_cvt_pk_bf16_f32 v112, v106, v107
	v_cvt_pk_bf16_f32 v113, v108, v109
	global_store_dwordx4 v[130:131], v[110:113], off offset:2048
	s_movk_i32 s14, 0x1000
	v_lshl_add_u64 v[114:115], v[130:131], 0, s[14:15]
	v_mul_f32_e32 v140, 0xbfb8aa3b, v134
	v_mul_f32_e32 v142, v134, v134
	v_pk_mul_f32 v[86:87], v[94:95], v[86:87]
	v_pk_mul_f32 v[88:89], v[96:97], v[88:89]
	v_pk_mul_f32 v[82:83], v[90:91], v[82:83]
	v_pk_mul_f32 v[84:85], v[92:93], v[84:85]
	v_pk_mul_f32 v[94:95], v[94:95], v[140:141] op_sel_hi:[1,0]
	v_pk_mul_f32 v[96:97], v[96:97], v[140:141] op_sel_hi:[1,0]
	v_pk_mul_f32 v[90:91], v[90:91], v[140:141] op_sel_hi:[1,0]
	v_pk_mul_f32 v[92:93], v[92:93], v[140:141] op_sel_hi:[1,0]
	v_exp_f32_e32 v94, v94
	v_exp_f32_e32 v95, v95
	v_exp_f32_e32 v96, v96
	v_exp_f32_e32 v97, v97
	v_exp_f32_e32 v90, v90
	v_exp_f32_e32 v91, v91
	v_exp_f32_e32 v92, v92
	v_exp_f32_e32 v93, v93
	v_pk_add_f32 v[94:95], v[94:95], v[144:145]
	v_pk_add_f32 v[96:97], v[96:97], v[144:145]
	v_pk_add_f32 v[90:91], v[90:91], v[144:145]
	v_pk_add_f32 v[92:93], v[92:93], v[144:145]
; DI u32x2 pk4(f32x4 v) { u32x2 r; r.x = cvt_pk(v[0], v[1]); r.y = cvt_pk(v[2], v[3]); return r; }
; DI float fexp2(float x) { return __builtin_amdgcn_exp2f(x); }
; DI float frcp(float x) { return __builtin_amdgcn_rcpf(x); }
; DI void gemm_phase(LAS unsigned char* lds, const GemmDesc& d, float* __restrict__ X) {
;     ...
;           const int row = pm * 256 + 128 * ai + 16 * m + rb; const float rs = rsl[128 * ai + 16 * m + rb]; const float c1 = -rs * LOG2E, c2 = rs * rs;
;           u32x2 hp[2];
; #pragma unroll
;           for (int n = 0; n < 2; ++n) {
;             const f32x4 G = acc[ai][0][m][n], U = acc[ai][1][m][n]; const f32x4 tt = G * c1; f32x4 ee;
; #pragma unroll
;             for (int j = 0; j < 4; ++j) ee[j] = fexp2(tt[j]);
;             const f32x4 dn = ee + 1.f; f32x4 rr;
; #pragma unroll
;             for (int j = 0; j < 4; ++j) rr[j] = frcp(dn[j]);
;             hp[n] = pk4((G * U) * (rr * c2));
;           }
;           { const int hc = pn * 128 + cb;
;             u32x4 hw; hw.x = hp[0].x; hw.y = hp[0].y; hw.z = hp[1].x; hw.w = hp[1].y;
;             *(u32x4*)(d.O0 + (size_t)(row >> 8) * (256 * FF) + (size_t)(hc >> 6) * (256 * 64) + (row & 255) * 64 + (hc & 63)) = hw; }
	v_rcp_f32_e32 v94, v94
	v_rcp_f32_e32 v95, v95
	v_rcp_f32_e32 v96, v96
	v_rcp_f32_e32 v97, v97
	v_rcp_f32_e32 v90, v90
	v_rcp_f32_e32 v91, v91
	v_rcp_f32_e32 v92, v92
	v_rcp_f32_e32 v93, v93
	v_pk_mul_f32 v[94:95], v[142:143], v[94:95] op_sel_hi:[0,1]
	v_pk_mul_f32 v[96:97], v[142:143], v[96:97] op_sel_hi:[0,1]
	v_pk_mul_f32 v[90:91], v[142:143], v[90:91] op_sel_hi:[0,1]
	v_pk_mul_f32 v[92:93], v[142:143], v[92:93] op_sel_hi:[0,1]
	v_pk_mul_f32 v[94:95], v[86:87], v[94:95]
	v_pk_mul_f32 v[96:97], v[88:89], v[96:97]
	v_pk_mul_f32 v[90:91], v[82:83], v[90:91]
	v_pk_mul_f32 v[92:93], v[84:85], v[92:93]
	v_cvt_pk_bf16_f32 v94, v94, v95
	v_cvt_pk_bf16_f32 v95, v96, v97
	v_cvt_pk_bf16_f32 v96, v90, v91
	v_cvt_pk_bf16_f32 v97, v92, v93
	global_store_dwordx4 v[114:115], v[94:97], off
	v_mul_f32_e32 v140, 0xbfb8aa3b, v135
	v_mul_f32_e32 v142, v135, v135
	v_pk_mul_f32 v[70:71], v[78:79], v[70:71]
	v_pk_mul_f32 v[72:73], v[80:81], v[72:73]
	v_pk_mul_f32 v[66:67], v[74:75], v[66:67]
	v_pk_mul_f32 v[68:69], v[76:77], v[68:69]
	v_pk_mul_f32 v[78:79], v[78:79], v[140:141] op_sel_hi:[1,0]
	v_pk_mul_f32 v[80:81], v[80:81], v[140:141] op_sel_hi:[1,0]
	v_pk_mul_f32 v[74:75], v[74:75], v[140:141] op_sel_hi:[1,0]
	v_pk_mul_f32 v[76:77], v[76:77], v[140:141] op_sel_hi:[1,0]
	v_exp_f32_e32 v78, v78
	v_exp_f32_e32 v79, v79
	v_exp_f32_e32 v80, v80
	v_exp_f32_e32 v81, v81
	v_exp_f32_e32 v74, v74
	v_exp_f32_e32 v75, v75
	v_exp_f32_e32 v76, v76
	v_exp_f32_e32 v77, v77
	v_pk_add_f32 v[78:79], v[78:79], v[144:145]
	v_pk_add_f32 v[80:81], v[80:81], v[144:145]
	v_pk_add_f32 v[74:75], v[74:75], v[144:145]
	v_pk_add_f32 v[76:77], v[76:77], v[144:145]
	v_rcp_f32_e32 v78, v78
	v_rcp_f32_e32 v79, v79
	v_rcp_f32_e32 v80, v80
	v_rcp_f32_e32 v81, v81
	v_rcp_f32_e32 v74, v74
	v_rcp_f32_e32 v75, v75
	v_rcp_f32_e32 v76, v76
	v_rcp_f32_e32 v77, v77
	v_pk_mul_f32 v[78:79], v[142:143], v[78:79] op_sel_hi:[0,1]
	v_pk_mul_f32 v[80:81], v[142:143], v[80:81] op_sel_hi:[0,1]
	v_pk_mul_f32 v[74:75], v[142:143], v[74:75] op_sel_hi:[0,1]
	v_pk_mul_f32 v[76:77], v[142:143], v[76:77] op_sel_hi:[0,1]
	v_pk_mul_f32 v[78:79], v[70:71], v[78:79]
	v_pk_mul_f32 v[80:81], v[72:73], v[80:81]
	v_pk_mul_f32 v[74:75], v[66:67], v[74:75]
	v_pk_mul_f32 v[76:77], v[68:69], v[76:77]
	v_cvt_pk_bf16_f32 v78, v78, v79
	v_cvt_pk_bf16_f32 v79, v80, v81
	v_cvt_pk_bf16_f32 v80, v74, v75
	v_cvt_pk_bf16_f32 v81, v76, v77
	global_store_dwordx4 v[114:115], v[78:81], off offset:2048
	s_movk_i32 s14, 0x4000
	v_lshl_add_u64 v[116:117], v[130:131], 0, s[14:15]
	v_mul_f32_e32 v140, 0xbfb8aa3b, v136
	v_mul_f32_e32 v142, v136, v136
	v_pk_mul_f32 v[54:55], v[62:63], v[54:55]
	v_pk_mul_f32 v[56:57], v[64:65], v[56:57]
	v_pk_mul_f32 v[50:51], v[58:59], v[50:51]
	v_pk_mul_f32 v[52:53], v[60:61], v[52:53]
	v_pk_mul_f32 v[62:63], v[62:63], v[140:141] op_sel_hi:[1,0]
	v_pk_mul_f32 v[64:65], v[64:65], v[140:141] op_sel_hi:[1,0]
	v_pk_mul_f32 v[58:59], v[58:59], v[140:141] op_sel_hi:[1,0]
	v_pk_mul_f32 v[60:61], v[60:61], v[140:141] op_sel_hi:[1,0]
	v_exp_f32_e32 v62, v62
	v_exp_f32_e32 v63, v63
	v_exp_f32_e32 v64, v64
	v_exp_f32_e32 v65, v65
	v_exp_f32_e32 v58, v58
	v_exp_f32_e32 v59, v59
	v_exp_f32_e32 v60, v60
	v_exp_f32_e32 v61, v61
	v_pk_add_f32 v[62:63], v[62:63], v[144:145]
	v_pk_add_f32 v[64:65], v[64:65], v[144:145]
	v_pk_add_f32 v[58:59], v[58:59], v[144:145]
	v_pk_add_f32 v[60:61], v[60:61], v[144:145]
	v_rcp_f32_e32 v62, v62
	v_rcp_f32_e32 v63, v63
	v_rcp_f32_e32 v64, v64
	v_rcp_f32_e32 v65, v65
	v_rcp_f32_e32 v58, v58
	v_rcp_f32_e32 v59, v59
	v_rcp_f32_e32 v60, v60
	v_rcp_f32_e32 v61, v61
	v_pk_mul_f32 v[62:63], v[142:143], v[62:63] op_sel_hi:[0,1]
	v_pk_mul_f32 v[64:65], v[142:143], v[64:65] op_sel_hi:[0,1]
	v_pk_mul_f32 v[58:59], v[142:143], v[58:59] op_sel_hi:[0,1]
	v_pk_mul_f32 v[60:61], v[142:143], v[60:61] op_sel_hi:[0,1]
	v_pk_mul_f32 v[62:63], v[54:55], v[62:63]
	v_pk_mul_f32 v[64:65], v[56:57], v[64:65]
	v_pk_mul_f32 v[58:59], v[50:51], v[58:59]
	v_pk_mul_f32 v[60:61], v[52:53], v[60:61]
	v_cvt_pk_bf16_f32 v62, v62, v63
	v_cvt_pk_bf16_f32 v63, v64, v65
	v_cvt_pk_bf16_f32 v64, v58, v59
	v_cvt_pk_bf16_f32 v65, v60, v61
	global_store_dwordx4 v[116:117], v[62:65], off
	v_mul_f32_e32 v140, 0xbfb8aa3b, v137
	v_mul_f32_e32 v142, v137, v137
	v_pk_mul_f32 v[38:39], v[46:47], v[38:39]
	v_pk_mul_f32 v[40:41], v[48:49], v[40:41]
	v_pk_mul_f32 v[34:35], v[42:43], v[34:35]
	v_pk_mul_f32 v[36:37], v[44:45], v[36:37]
	v_pk_mul_f32 v[46:47], v[46:47], v[140:141] op_sel_hi:[1,0]
	v_pk_mul_f32 v[48:49], v[48:49], v[140:141] op_sel_hi:[1,0]
	v_pk_mul_f32 v[42:43], v[42:43], v[140:141] op_sel_hi:[1,0]
; DI u32x2 pk4(f32x4 v) { u32x2 r; r.x = cvt_pk(v[0], v[1]); r.y = cvt_pk(v[2], v[3]); return r; }
; DI float fexp2(float x) { return __builtin_amdgcn_exp2f(x); }
; DI float frcp(float x) { return __builtin_amdgcn_rcpf(x); }
; DI void gemm_phase(LAS unsigned char* lds, const GemmDesc& d, float* __restrict__ X) {
;     ...
;           const int row = pm * 256 + 128 * ai + 16 * m + rb; const float rs = rsl[128 * ai + 16 * m + rb]; const float c1 = -rs * LOG2E, c2 = rs * rs;
;           u32x2 hp[2];
; #pragma unroll
;           for (int n = 0; n < 2; ++n) {
;             const f32x4 G = acc[ai][0][m][n], U = acc[ai][1][m][n]; const f32x4 tt = G * c1; f32x4 ee;
; #pragma unroll
;             for (int j = 0; j < 4; ++j) ee[j] = fexp2(tt[j]);
;             const f32x4 dn = ee + 1.f; f32x4 rr;
; #pragma unroll
;             for (int j = 0; j < 4; ++j) rr[j] = frcp(dn[j]);
;             hp[n] = pk4((G * U) * (rr * c2));
;           }
;           { const int hc = pn * 128 + cb;
;             u32x4 hw; hw.x = hp[0].x; hw.y = hp[0].y; hw.z = hp[1].x; hw.w = hp[1].y;
;             *(u32x4*)(d.O0 + (size_t)(row >> 8) * (256 * FF) + (size_t)(hc >> 6) * (256 * 64) + (row & 255) * 64 + (hc & 63)) = hw; }
	v_pk_mul_f32 v[44:45], v[44:45], v[140:141] op_sel_hi:[1,0]
	v_exp_f32_e32 v46, v46
	v_exp_f32_e32 v47, v47
	v_exp_f32_e32 v48, v48
	v_exp_f32_e32 v49, v49
	v_exp_f32_e32 v42, v42
	v_exp_f32_e32 v43, v43
	v_exp_f32_e32 v44, v44
	v_exp_f32_e32 v45, v45
	v_pk_add_f32 v[46:47], v[46:47], v[144:145]
	v_pk_add_f32 v[48:49], v[48:49], v[144:145]
	v_pk_add_f32 v[42:43], v[42:43], v[144:145]
	v_pk_add_f32 v[44:45], v[44:45], v[144:145]
	v_rcp_f32_e32 v46, v46
	v_rcp_f32_e32 v47, v47
	v_rcp_f32_e32 v48, v48
	v_rcp_f32_e32 v49, v49
	v_rcp_f32_e32 v42, v42
	v_rcp_f32_e32 v43, v43
	v_rcp_f32_e32 v44, v44
	v_rcp_f32_e32 v45, v45
	v_pk_mul_f32 v[46:47], v[142:143], v[46:47] op_sel_hi:[0,1]
	v_pk_mul_f32 v[48:49], v[142:143], v[48:49] op_sel_hi:[0,1]
	v_pk_mul_f32 v[42:43], v[142:143], v[42:43] op_sel_hi:[0,1]
	v_pk_mul_f32 v[44:45], v[142:143], v[44:45] op_sel_hi:[0,1]
	v_pk_mul_f32 v[46:47], v[38:39], v[46:47]
	v_pk_mul_f32 v[48:49], v[40:41], v[48:49]
	v_pk_mul_f32 v[42:43], v[34:35], v[42:43]
	v_pk_mul_f32 v[44:45], v[36:37], v[44:45]
	v_cvt_pk_bf16_f32 v46, v46, v47
	v_cvt_pk_bf16_f32 v47, v48, v49
	v_cvt_pk_bf16_f32 v48, v42, v43
	v_cvt_pk_bf16_f32 v49, v44, v45
	global_store_dwordx4 v[116:117], v[46:49], off offset:2048
	s_movk_i32 s14, 0x5000
	v_lshl_add_u64 v[118:119], v[130:131], 0, s[14:15]
	v_mul_f32_e32 v140, 0xbfb8aa3b, v138
	v_mul_f32_e32 v142, v138, v138
	v_pk_mul_f32 v[22:23], v[30:31], v[22:23]
	v_pk_mul_f32 v[24:25], v[32:33], v[24:25]
	v_pk_mul_f32 v[18:19], v[26:27], v[18:19]
	v_pk_mul_f32 v[20:21], v[28:29], v[20:21]
	v_pk_mul_f32 v[30:31], v[30:31], v[140:141] op_sel_hi:[1,0]
	v_pk_mul_f32 v[32:33], v[32:33], v[140:141] op_sel_hi:[1,0]
	v_pk_mul_f32 v[26:27], v[26:27], v[140:141] op_sel_hi:[1,0]
	v_pk_mul_f32 v[28:29], v[28:29], v[140:141] op_sel_hi:[1,0]
	v_exp_f32_e32 v30, v30
	v_exp_f32_e32 v31, v31
	v_exp_f32_e32 v32, v32
	v_exp_f32_e32 v33, v33
	v_exp_f32_e32 v26, v26
	v_exp_f32_e32 v27, v27
	v_exp_f32_e32 v28, v28
	v_exp_f32_e32 v29, v29
	v_pk_add_f32 v[30:31], v[30:31], v[144:145]
	v_pk_add_f32 v[32:33], v[32:33], v[144:145]
	v_pk_add_f32 v[26:27], v[26:27], v[144:145]
	v_pk_add_f32 v[28:29], v[28:29], v[144:145]
	v_rcp_f32_e32 v30, v30
	v_rcp_f32_e32 v31, v31
	v_rcp_f32_e32 v32, v32
	v_rcp_f32_e32 v33, v33
	v_rcp_f32_e32 v26, v26
	v_rcp_f32_e32 v27, v27
	v_rcp_f32_e32 v28, v28
	v_rcp_f32_e32 v29, v29
	v_pk_mul_f32 v[30:31], v[142:143], v[30:31] op_sel_hi:[0,1]
	v_pk_mul_f32 v[32:33], v[142:143], v[32:33] op_sel_hi:[0,1]
	v_pk_mul_f32 v[26:27], v[142:143], v[26:27] op_sel_hi:[0,1]
	v_pk_mul_f32 v[28:29], v[142:143], v[28:29] op_sel_hi:[0,1]
	v_pk_mul_f32 v[30:31], v[22:23], v[30:31]
	v_pk_mul_f32 v[32:33], v[24:25], v[32:33]
	v_pk_mul_f32 v[26:27], v[18:19], v[26:27]
	v_pk_mul_f32 v[28:29], v[20:21], v[28:29]
	v_cvt_pk_bf16_f32 v30, v30, v31
	v_cvt_pk_bf16_f32 v31, v32, v33
	v_cvt_pk_bf16_f32 v32, v26, v27
	v_cvt_pk_bf16_f32 v33, v28, v29
	global_store_dwordx4 v[118:119], v[30:33], off
	v_mul_f32_e32 v140, 0xbfb8aa3b, v139
	v_mul_f32_e32 v142, v139, v139
	v_pk_mul_f32 v[6:7], v[14:15], v[6:7]
	v_pk_mul_f32 v[8:9], v[16:17], v[8:9]
	v_pk_mul_f32 v[2:3], v[10:11], v[2:3]
	v_pk_mul_f32 v[4:5], v[12:13], v[4:5]
	v_pk_mul_f32 v[14:15], v[14:15], v[140:141] op_sel_hi:[1,0]
	v_pk_mul_f32 v[16:17], v[16:17], v[140:141] op_sel_hi:[1,0]
	v_pk_mul_f32 v[10:11], v[10:11], v[140:141] op_sel_hi:[1,0]
	v_pk_mul_f32 v[12:13], v[12:13], v[140:141] op_sel_hi:[1,0]
	v_exp_f32_e32 v14, v14
	v_exp_f32_e32 v15, v15
	v_exp_f32_e32 v16, v16
	v_exp_f32_e32 v17, v17
	v_exp_f32_e32 v10, v10
	v_exp_f32_e32 v11, v11
	v_exp_f32_e32 v12, v12
	v_exp_f32_e32 v13, v13
	v_pk_add_f32 v[14:15], v[14:15], v[144:145]
	v_pk_add_f32 v[16:17], v[16:17], v[144:145]
	v_pk_add_f32 v[10:11], v[10:11], v[144:145]
	v_pk_add_f32 v[12:13], v[12:13], v[144:145]
	v_rcp_f32_e32 v14, v14
	v_rcp_f32_e32 v15, v15
	v_rcp_f32_e32 v16, v16
	v_rcp_f32_e32 v17, v17
	v_rcp_f32_e32 v10, v10
	v_rcp_f32_e32 v11, v11
	v_rcp_f32_e32 v12, v12
	v_rcp_f32_e32 v13, v13
	v_pk_mul_f32 v[14:15], v[142:143], v[14:15] op_sel_hi:[0,1]
	v_pk_mul_f32 v[16:17], v[142:143], v[16:17] op_sel_hi:[0,1]
	v_pk_mul_f32 v[10:11], v[142:143], v[10:11] op_sel_hi:[0,1]
	v_pk_mul_f32 v[12:13], v[142:143], v[12:13] op_sel_hi:[0,1]
	v_pk_mul_f32 v[14:15], v[6:7], v[14:15]
	v_pk_mul_f32 v[16:17], v[8:9], v[16:17]
	v_pk_mul_f32 v[10:11], v[2:3], v[10:11]
	v_pk_mul_f32 v[12:13], v[4:5], v[12:13]
	v_cvt_pk_bf16_f32 v14, v14, v15
	v_cvt_pk_bf16_f32 v15, v16, v17
	v_cvt_pk_bf16_f32 v16, v10, v11
	v_cvt_pk_bf16_f32 v17, v12, v13
	global_store_dwordx4 v[118:119], v[14:17], off offset:2048
	s_mov_b64 s[44:45], 0
